# baseline (speedup 1.0000x reference)
.LBB0_204:
	s_lshl_b32 s12, s50, 8
	s_cmp_eq_u32 s50, 2
	s_cselect_b32 s56, 0, s12
	s_cselect_b32 s13, s73, s80
	s_cselect_b32 s43, s72, s35
	s_cselect_b32 s41, 8, 9
	s_ashr_i32 s57, s56, 31
	s_lshl_b32 s12, s50, 2
	v_lshl_add_u32 v160, s48, 8, v135
	s_or_b32 s48, s12, s86
	s_lshl_b64 s[50:51], s[56:57], 1
	s_add_u32 s12, s43, s50
	s_addc_u32 s13, s13, s51
	s_add_u32 s50, s12, s96
	s_addc_u32 s51, s13, 0
	v_ashrrev_i32_e32 v161, 31, v160
	v_lshl_add_u64 v[162:163], s[50:51], 0, v[132:133]
	v_lshlrev_b64 v[164:165], s41, v[160:161]
	v_mul_f32_e32 v157, v125, v125
	v_lshl_add_u64 v[164:165], v[164:165], 1, v[162:163]
	v_fmac_f32_e32 v157, v124, v124
	v_mbcnt_lo_u32_b32 v252, -1, 0
	v_mbcnt_hi_u32_b32 v252, -1, v252
	v_and_b32_e32 v252, 16, v252
	v_lshrrev_b32_e32 v253, 1, v252
	v_add_u32_e32 v252, v252, v253
	v_mov_b32_e32 v253, 0
	v_cvt_pk_bf16_f32 v244, v124, v125
	v_cvt_pk_bf16_f32 v245, v126, v127
	v_mul_f32_e32 v159, v127, v127
	s_nop 0
	v_mul_f32_e32 v124, v121, v121
	v_mul_f32_e32 v125, v123, v123
	v_fmac_f32_e32 v159, v126, v126
	v_fmac_f32_e32 v124, v120, v120
	v_fmac_f32_e32 v125, v122, v122
	v_add_f32_e32 v157, v157, v159
	v_add_f32_e32 v124, v124, v125
	v_add_f32_e32 v125, v157, v124
	v_cvt_pk_bf16_f32 v246, v120, v121
	v_mul_f32_e32 v120, v117, v117
	v_mul_f32_e32 v121, v119, v119
	v_fmac_f32_e32 v120, v116, v116
	v_fmac_f32_e32 v121, v118, v118
	v_add_f32_e32 v120, v120, v121
	v_add_f32_e32 v120, v125, v120
	v_mul_f32_e32 v121, v113, v113
	v_mul_f32_e32 v125, v115, v115
	v_fmac_f32_e32 v121, v112, v112
	v_fmac_f32_e32 v125, v114, v114
	v_add_f32_e32 v121, v121, v125
	v_and_b32_e32 v125, 64, v189
	v_add_f32_e32 v121, v120, v121
	v_xor_b32_e32 v120, 16, v189
	v_add_u32_e32 v126, 64, v125
	v_cmp_lt_i32_e32 vcc, v120, v126
	v_cvt_pk_bf16_f32 v247, v122, v123
	s_nop 1
	v_permlane16_swap_b32_e32 v244, v246
	v_permlane16_swap_b32_e32 v245, v247
	v_lshl_add_u64 v[242:243], v[164:165], 0, v[252:253]
	global_store_dwordx4 v[242:243], v[244:247], off sc0 sc1
	v_cvt_pk_bf16_f32 v248, v116, v117
	v_xor_b32_e32 v116, 32, v189
	v_cndmask_b32_e32 v120, v189, v120, vcc
	v_lshlrev_b32_e32 v120, 2, v120
	ds_bpermute_b32 v127, v120, v121
	v_cmp_lt_i32_e32 vcc, v116, v126
	v_cvt_pk_bf16_f32 v249, v118, v119
	s_ashr_i32 s49, s48, 31
	s_nop 0
	v_cndmask_b32_e32 v116, v189, v116, vcc
	s_waitcnt lgkmcnt(0)
	v_add_f32_e32 v117, v121, v127
	v_lshlrev_b32_e32 v116, 2, v116
	ds_bpermute_b32 v118, v116, v117
	v_cvt_pk_bf16_f32 v250, v112, v113
	v_cvt_pk_bf16_f32 v251, v114, v115
	s_nop 1
	v_permlane16_swap_b32_e32 v248, v250
	v_permlane16_swap_b32_e32 v249, v251
	v_lshl_add_u64 v[242:243], v[164:165], 0, v[252:253]
	global_store_dwordx4 v[242:243], v[248:251], off offset:256 sc0 sc1
	s_and_saveexec_b64 s[50:51], s[4:5]
	s_cbranch_execz .LBB0_206
	v_lshlrev_b64 v[112:113], 6, v[160:161]
	v_lshl_add_u64 v[112:113], s[60:61], 0, v[112:113]
	v_lshl_add_u64 v[112:113], s[48:49], 2, v[112:113]
	s_waitcnt lgkmcnt(0)
	v_add_f32_e32 v114, v117, v118
	global_store_dword v[112:113], v114, off
.LBB0_206:
	s_or_b64 exec, exec, s[50:51]
	v_or_b32_e32 v112, 16, v160
	v_ashrrev_i32_e32 v113, 31, v112
	v_lshlrev_b64 v[114:115], s41, v[112:113]
	v_mul_f32_e32 v117, v109, v109
	v_lshl_add_u64 v[114:115], v[114:115], 1, v[162:163]
	v_fmac_f32_e32 v117, v108, v108
	v_mbcnt_lo_u32_b32 v252, -1, 0
	v_mbcnt_hi_u32_b32 v252, -1, v252
	v_and_b32_e32 v252, 16, v252
	v_lshrrev_b32_e32 v253, 1, v252
	v_add_u32_e32 v252, v252, v253
	v_mov_b32_e32 v253, 0
	v_cvt_pk_bf16_f32 v244, v108, v109
	v_cvt_pk_bf16_f32 v245, v110, v111
	s_nop 0
	v_mul_f32_e32 v108, v105, v105
	v_mul_f32_e32 v109, v107, v107
	s_waitcnt lgkmcnt(0)
	v_mul_f32_e32 v118, v111, v111
	v_fmac_f32_e32 v108, v104, v104
	v_fmac_f32_e32 v109, v106, v106
	v_fmac_f32_e32 v118, v110, v110
	v_add_f32_e32 v108, v108, v109
	v_cvt_pk_bf16_f32 v246, v104, v105
	v_mul_f32_e32 v105, v101, v101
	v_mul_f32_e32 v109, v103, v103
	v_add_f32_e32 v117, v117, v118
	v_fmac_f32_e32 v105, v100, v100
	v_fmac_f32_e32 v109, v102, v102
	v_add_f32_e32 v108, v117, v108
	v_add_f32_e32 v105, v105, v109
	v_add_f32_e32 v105, v108, v105
	v_mul_f32_e32 v108, v97, v97
	v_mul_f32_e32 v109, v99, v99
	v_fmac_f32_e32 v108, v96, v96
	v_fmac_f32_e32 v109, v98, v98
	v_add_f32_e32 v108, v108, v109
	v_add_f32_e32 v108, v105, v108
	ds_bpermute_b32 v109, v120, v108
	v_cvt_pk_bf16_f32 v247, v106, v107
	s_nop 1
	v_permlane16_swap_b32_e32 v244, v246
	v_permlane16_swap_b32_e32 v245, v247
	v_lshl_add_u64 v[242:243], v[114:115], 0, v[252:253]
	global_store_dwordx4 v[242:243], v[244:247], off sc0 sc1
	v_cvt_pk_bf16_f32 v248, v100, v101
	v_cvt_pk_bf16_f32 v249, v102, v103
	s_waitcnt lgkmcnt(0)
	v_add_f32_e32 v100, v108, v109
	ds_bpermute_b32 v101, v116, v100
	s_nop 0
	v_cvt_pk_bf16_f32 v250, v96, v97
	v_cvt_pk_bf16_f32 v251, v98, v99
	s_nop 1
	v_permlane16_swap_b32_e32 v248, v250
	v_permlane16_swap_b32_e32 v249, v251
	v_lshl_add_u64 v[242:243], v[114:115], 0, v[252:253]
	global_store_dwordx4 v[242:243], v[248:251], off offset:256 sc0 sc1
	s_and_saveexec_b64 s[50:51], s[4:5]
	s_cbranch_execz .LBB0_208
	v_lshlrev_b64 v[96:97], 6, v[112:113]
	v_lshl_add_u64 v[96:97], s[60:61], 0, v[96:97]
	v_lshl_add_u64 v[96:97], s[48:49], 2, v[96:97]
	s_waitcnt lgkmcnt(0)
	v_add_f32_e32 v98, v100, v101
	global_store_dword v[96:97], v98, off
.LBB0_208:
	s_or_b64 exec, exec, s[50:51]
	v_or_b32_e32 v96, 32, v160
	v_ashrrev_i32_e32 v97, 31, v96
	v_lshlrev_b64 v[98:99], s41, v[96:97]
	v_mul_f32_e32 v100, v93, v93
	v_lshl_add_u64 v[98:99], v[98:99], 1, v[162:163]
	v_fmac_f32_e32 v100, v92, v92
	v_mbcnt_lo_u32_b32 v252, -1, 0
	v_mbcnt_hi_u32_b32 v252, -1, v252
	v_and_b32_e32 v252, 16, v252
	v_lshrrev_b32_e32 v253, 1, v252
	v_add_u32_e32 v252, v252, v253
	v_mov_b32_e32 v253, 0
	v_cvt_pk_bf16_f32 v244, v92, v93
	v_cvt_pk_bf16_f32 v245, v94, v95
	s_nop 0
	v_mul_f32_e32 v92, v89, v89
	v_mul_f32_e32 v93, v91, v91
	s_waitcnt lgkmcnt(0)
	v_mul_f32_e32 v101, v95, v95
	v_fmac_f32_e32 v92, v88, v88
	v_fmac_f32_e32 v93, v90, v90
	v_fmac_f32_e32 v101, v94, v94
	v_add_f32_e32 v92, v92, v93
	v_cvt_pk_bf16_f32 v246, v88, v89
	v_mul_f32_e32 v89, v85, v85
	v_mul_f32_e32 v93, v87, v87
	v_add_f32_e32 v100, v100, v101
	v_fmac_f32_e32 v89, v84, v84
	v_fmac_f32_e32 v93, v86, v86
	v_add_f32_e32 v92, v100, v92
	v_add_f32_e32 v89, v89, v93
	v_add_f32_e32 v89, v92, v89
	v_mul_f32_e32 v92, v81, v81
	v_mul_f32_e32 v93, v83, v83
	v_fmac_f32_e32 v92, v80, v80
	v_fmac_f32_e32 v93, v82, v82
	v_add_f32_e32 v92, v92, v93
	v_add_f32_e32 v92, v89, v92
	ds_bpermute_b32 v93, v120, v92
	v_cvt_pk_bf16_f32 v247, v90, v91
	s_nop 1
	v_permlane16_swap_b32_e32 v244, v246
	v_permlane16_swap_b32_e32 v245, v247
	v_lshl_add_u64 v[242:243], v[98:99], 0, v[252:253]
	global_store_dwordx4 v[242:243], v[244:247], off sc0 sc1
	v_cvt_pk_bf16_f32 v248, v84, v85
	v_cvt_pk_bf16_f32 v249, v86, v87
	s_waitcnt lgkmcnt(0)
	v_add_f32_e32 v84, v92, v93
	ds_bpermute_b32 v85, v116, v84
	s_nop 0
	v_cvt_pk_bf16_f32 v250, v80, v81
	v_cvt_pk_bf16_f32 v251, v82, v83
	s_nop 1
	v_permlane16_swap_b32_e32 v248, v250
	v_permlane16_swap_b32_e32 v249, v251
	v_lshl_add_u64 v[242:243], v[98:99], 0, v[252:253]
	global_store_dwordx4 v[242:243], v[248:251], off offset:256 sc0 sc1
	s_and_saveexec_b64 s[50:51], s[4:5]
	s_cbranch_execz .LBB0_210
	v_lshlrev_b64 v[80:81], 6, v[96:97]
	v_lshl_add_u64 v[80:81], s[60:61], 0, v[80:81]
	v_lshl_add_u64 v[80:81], s[48:49], 2, v[80:81]
	s_waitcnt lgkmcnt(0)
	v_add_f32_e32 v82, v84, v85
	global_store_dword v[80:81], v82, off
.LBB0_210:
	s_or_b64 exec, exec, s[50:51]
	v_or_b32_e32 v80, 48, v160
	v_ashrrev_i32_e32 v81, 31, v80
	v_lshlrev_b64 v[82:83], s41, v[80:81]
	v_mul_f32_e32 v84, v77, v77
	v_lshl_add_u64 v[82:83], v[82:83], 1, v[162:163]
	v_fmac_f32_e32 v84, v76, v76
	v_mbcnt_lo_u32_b32 v252, -1, 0
	v_mbcnt_hi_u32_b32 v252, -1, v252
	v_and_b32_e32 v252, 16, v252
	v_lshrrev_b32_e32 v253, 1, v252
	v_add_u32_e32 v252, v252, v253
	v_mov_b32_e32 v253, 0
	v_cvt_pk_bf16_f32 v244, v76, v77
	v_cvt_pk_bf16_f32 v245, v78, v79
	s_nop 0
	v_mul_f32_e32 v76, v73, v73
	v_mul_f32_e32 v77, v75, v75
	s_waitcnt lgkmcnt(0)
	v_mul_f32_e32 v85, v79, v79
	v_fmac_f32_e32 v76, v72, v72
	v_fmac_f32_e32 v77, v74, v74
	v_fmac_f32_e32 v85, v78, v78
	v_add_f32_e32 v76, v76, v77
	v_cvt_pk_bf16_f32 v246, v72, v73
	v_mul_f32_e32 v73, v69, v69
	v_mul_f32_e32 v77, v71, v71
	v_add_f32_e32 v84, v84, v85
	v_fmac_f32_e32 v73, v68, v68
	v_fmac_f32_e32 v77, v70, v70
	v_add_f32_e32 v76, v84, v76
	v_add_f32_e32 v73, v73, v77
	v_add_f32_e32 v73, v76, v73
	v_mul_f32_e32 v76, v65, v65
	v_mul_f32_e32 v77, v67, v67
	v_fmac_f32_e32 v76, v64, v64
	v_fmac_f32_e32 v77, v66, v66
	v_add_f32_e32 v76, v76, v77
	v_add_f32_e32 v76, v73, v76
	ds_bpermute_b32 v77, v120, v76
	v_cvt_pk_bf16_f32 v247, v74, v75
	s_nop 1
	v_permlane16_swap_b32_e32 v244, v246
	v_permlane16_swap_b32_e32 v245, v247
	v_lshl_add_u64 v[242:243], v[82:83], 0, v[252:253]
	global_store_dwordx4 v[242:243], v[244:247], off sc0 sc1
	v_cvt_pk_bf16_f32 v248, v68, v69
	v_cvt_pk_bf16_f32 v249, v70, v71
	s_waitcnt lgkmcnt(0)
	v_add_f32_e32 v68, v76, v77
	ds_bpermute_b32 v69, v116, v68
	s_nop 0
	v_cvt_pk_bf16_f32 v250, v64, v65
	v_cvt_pk_bf16_f32 v251, v66, v67
	s_nop 1
	v_permlane16_swap_b32_e32 v248, v250
	v_permlane16_swap_b32_e32 v249, v251
	v_lshl_add_u64 v[242:243], v[82:83], 0, v[252:253]
	global_store_dwordx4 v[242:243], v[248:251], off offset:256 sc0 sc1
	s_and_saveexec_b64 s[50:51], s[4:5]
	s_cbranch_execz .LBB0_212
	v_lshlrev_b64 v[64:65], 6, v[80:81]
	v_lshl_add_u64 v[64:65], s[60:61], 0, v[64:65]
	v_lshl_add_u64 v[64:65], s[48:49], 2, v[64:65]
	s_waitcnt lgkmcnt(0)
	v_add_f32_e32 v66, v68, v69
	global_store_dword v[64:65], v66, off
.LBB0_212:
	s_or_b64 exec, exec, s[50:51]
	v_add_u32_e32 v64, 0x80, v160
	v_ashrrev_i32_e32 v65, 31, v64
	v_lshlrev_b64 v[66:67], s41, v[64:65]
	v_mul_f32_e32 v68, v61, v61
	v_lshl_add_u64 v[66:67], v[66:67], 1, v[162:163]
	v_fmac_f32_e32 v68, v60, v60
	v_mbcnt_lo_u32_b32 v252, -1, 0
	v_mbcnt_hi_u32_b32 v252, -1, v252
	v_and_b32_e32 v252, 16, v252
	v_lshrrev_b32_e32 v253, 1, v252
	v_add_u32_e32 v252, v252, v253
	v_mov_b32_e32 v253, 0
	v_cvt_pk_bf16_f32 v244, v60, v61
	v_cvt_pk_bf16_f32 v245, v62, v63
	s_nop 0
	v_mul_f32_e32 v60, v57, v57
	v_mul_f32_e32 v61, v59, v59
	s_waitcnt lgkmcnt(0)
	v_mul_f32_e32 v69, v63, v63
	v_fmac_f32_e32 v60, v56, v56
	v_fmac_f32_e32 v61, v58, v58
	v_fmac_f32_e32 v69, v62, v62
	v_add_f32_e32 v60, v60, v61
	v_cvt_pk_bf16_f32 v246, v56, v57
	v_mul_f32_e32 v57, v53, v53
	v_mul_f32_e32 v61, v55, v55
	v_add_f32_e32 v68, v68, v69
	v_fmac_f32_e32 v57, v52, v52
	v_fmac_f32_e32 v61, v54, v54
	v_add_f32_e32 v60, v68, v60
	v_add_f32_e32 v57, v57, v61
	v_add_f32_e32 v57, v60, v57
	v_mul_f32_e32 v60, v49, v49
	v_mul_f32_e32 v61, v51, v51
	v_fmac_f32_e32 v60, v48, v48
	v_fmac_f32_e32 v61, v50, v50
	v_add_f32_e32 v60, v60, v61
	v_add_f32_e32 v60, v57, v60
	ds_bpermute_b32 v61, v120, v60
	v_cvt_pk_bf16_f32 v247, v58, v59
	s_nop 1
	v_permlane16_swap_b32_e32 v244, v246
	v_permlane16_swap_b32_e32 v245, v247
	v_lshl_add_u64 v[242:243], v[66:67], 0, v[252:253]
	global_store_dwordx4 v[242:243], v[244:247], off sc0 sc1
	v_cvt_pk_bf16_f32 v248, v52, v53
	v_cvt_pk_bf16_f32 v249, v54, v55
	s_waitcnt lgkmcnt(0)
	v_add_f32_e32 v52, v60, v61
	ds_bpermute_b32 v53, v116, v52
	s_nop 0
	v_cvt_pk_bf16_f32 v250, v48, v49
	v_cvt_pk_bf16_f32 v251, v50, v51
	s_nop 1
	v_permlane16_swap_b32_e32 v248, v250
	v_permlane16_swap_b32_e32 v249, v251
	v_lshl_add_u64 v[242:243], v[66:67], 0, v[252:253]
	global_store_dwordx4 v[242:243], v[248:251], off offset:256 sc0 sc1
	s_and_saveexec_b64 s[50:51], s[4:5]
	s_cbranch_execz .LBB0_214
	v_lshlrev_b64 v[48:49], 6, v[64:65]
	v_lshl_add_u64 v[48:49], s[60:61], 0, v[48:49]
	v_lshl_add_u64 v[48:49], s[48:49], 2, v[48:49]
	s_waitcnt lgkmcnt(0)
	v_add_f32_e32 v50, v52, v53
	global_store_dword v[48:49], v50, off
.LBB0_214:
	s_or_b64 exec, exec, s[50:51]
	v_add_u32_e32 v48, 0x90, v160
	v_ashrrev_i32_e32 v49, 31, v48
	v_lshlrev_b64 v[50:51], s41, v[48:49]
	v_mul_f32_e32 v52, v45, v45
	v_lshl_add_u64 v[50:51], v[50:51], 1, v[162:163]
	v_fmac_f32_e32 v52, v44, v44
	v_mbcnt_lo_u32_b32 v252, -1, 0
	v_mbcnt_hi_u32_b32 v252, -1, v252
	v_and_b32_e32 v252, 16, v252
	v_lshrrev_b32_e32 v253, 1, v252
	v_add_u32_e32 v252, v252, v253
	v_mov_b32_e32 v253, 0
	v_cvt_pk_bf16_f32 v244, v44, v45
	v_cvt_pk_bf16_f32 v245, v46, v47
	s_nop 0
	v_mul_f32_e32 v44, v41, v41
	v_mul_f32_e32 v45, v43, v43
	s_waitcnt lgkmcnt(0)
	v_mul_f32_e32 v53, v47, v47
	v_fmac_f32_e32 v44, v40, v40
	v_fmac_f32_e32 v45, v42, v42
	v_fmac_f32_e32 v53, v46, v46
	v_add_f32_e32 v44, v44, v45
	v_cvt_pk_bf16_f32 v246, v40, v41
	v_mul_f32_e32 v41, v37, v37
	v_mul_f32_e32 v45, v39, v39
	v_add_f32_e32 v52, v52, v53
	v_fmac_f32_e32 v41, v36, v36
	v_fmac_f32_e32 v45, v38, v38
	v_add_f32_e32 v44, v52, v44
	v_add_f32_e32 v41, v41, v45
	v_add_f32_e32 v41, v44, v41
	v_mul_f32_e32 v44, v33, v33
	v_mul_f32_e32 v45, v35, v35
	v_fmac_f32_e32 v44, v32, v32
	v_fmac_f32_e32 v45, v34, v34
	v_add_f32_e32 v44, v44, v45
	v_add_f32_e32 v44, v41, v44
	ds_bpermute_b32 v45, v120, v44
	v_cvt_pk_bf16_f32 v247, v42, v43
	s_nop 1
	v_permlane16_swap_b32_e32 v244, v246
	v_permlane16_swap_b32_e32 v245, v247
	v_lshl_add_u64 v[242:243], v[50:51], 0, v[252:253]
	global_store_dwordx4 v[242:243], v[244:247], off sc0 sc1
	v_cvt_pk_bf16_f32 v248, v36, v37
	v_cvt_pk_bf16_f32 v249, v38, v39
	s_waitcnt lgkmcnt(0)
	v_add_f32_e32 v36, v44, v45
	ds_bpermute_b32 v37, v116, v36
	s_nop 0
	v_cvt_pk_bf16_f32 v250, v32, v33
	v_cvt_pk_bf16_f32 v251, v34, v35
	s_nop 1
	v_permlane16_swap_b32_e32 v248, v250
	v_permlane16_swap_b32_e32 v249, v251
	v_lshl_add_u64 v[242:243], v[50:51], 0, v[252:253]
	global_store_dwordx4 v[242:243], v[248:251], off offset:256 sc0 sc1
	s_and_saveexec_b64 s[50:51], s[4:5]
	s_cbranch_execz .LBB0_216
	v_lshlrev_b64 v[32:33], 6, v[48:49]
	v_lshl_add_u64 v[32:33], s[60:61], 0, v[32:33]
	v_lshl_add_u64 v[32:33], s[48:49], 2, v[32:33]
	s_waitcnt lgkmcnt(0)
	v_add_f32_e32 v34, v36, v37
	global_store_dword v[32:33], v34, off
.LBB0_216:
	s_or_b64 exec, exec, s[50:51]
	v_add_u32_e32 v32, 0xa0, v160
	v_ashrrev_i32_e32 v33, 31, v32
	v_lshlrev_b64 v[34:35], s41, v[32:33]
	v_mul_f32_e32 v36, v29, v29
	v_lshl_add_u64 v[34:35], v[34:35], 1, v[162:163]
	v_fmac_f32_e32 v36, v28, v28
	v_mbcnt_lo_u32_b32 v252, -1, 0
	v_mbcnt_hi_u32_b32 v252, -1, v252
	v_and_b32_e32 v252, 16, v252
	v_lshrrev_b32_e32 v253, 1, v252
	v_add_u32_e32 v252, v252, v253
	v_mov_b32_e32 v253, 0
	v_cvt_pk_bf16_f32 v244, v28, v29
	v_cvt_pk_bf16_f32 v245, v30, v31
	s_nop 0
	v_mul_f32_e32 v28, v25, v25
	v_mul_f32_e32 v29, v27, v27
	s_waitcnt lgkmcnt(0)
	v_mul_f32_e32 v37, v31, v31
	v_fmac_f32_e32 v28, v24, v24
	v_fmac_f32_e32 v29, v26, v26
	v_fmac_f32_e32 v37, v30, v30
	v_add_f32_e32 v28, v28, v29
	v_cvt_pk_bf16_f32 v246, v24, v25
	v_mul_f32_e32 v25, v21, v21
	v_mul_f32_e32 v29, v23, v23
	v_add_f32_e32 v36, v36, v37
	v_fmac_f32_e32 v25, v20, v20
	v_fmac_f32_e32 v29, v22, v22
	v_add_f32_e32 v28, v36, v28
	v_add_f32_e32 v25, v25, v29
	v_add_f32_e32 v25, v28, v25
	v_mul_f32_e32 v28, v17, v17
	v_mul_f32_e32 v29, v19, v19
	v_fmac_f32_e32 v28, v16, v16
	v_fmac_f32_e32 v29, v18, v18
	v_add_f32_e32 v28, v28, v29
	v_add_f32_e32 v28, v25, v28
	ds_bpermute_b32 v29, v120, v28
	v_cvt_pk_bf16_f32 v247, v26, v27
	s_nop 1
	v_permlane16_swap_b32_e32 v244, v246
	v_permlane16_swap_b32_e32 v245, v247
	v_lshl_add_u64 v[242:243], v[34:35], 0, v[252:253]
	global_store_dwordx4 v[242:243], v[244:247], off sc0 sc1
	v_cvt_pk_bf16_f32 v248, v20, v21
	v_cvt_pk_bf16_f32 v249, v22, v23
	s_waitcnt lgkmcnt(0)
	v_add_f32_e32 v20, v28, v29
	ds_bpermute_b32 v21, v116, v20
	s_nop 0
	v_cvt_pk_bf16_f32 v250, v16, v17
	v_cvt_pk_bf16_f32 v251, v18, v19
	s_nop 1
	v_permlane16_swap_b32_e32 v248, v250
	v_permlane16_swap_b32_e32 v249, v251
	v_lshl_add_u64 v[242:243], v[34:35], 0, v[252:253]
	global_store_dwordx4 v[242:243], v[248:251], off offset:256 sc0 sc1
	s_and_saveexec_b64 s[50:51], s[4:5]
	s_cbranch_execz .LBB0_218
	v_lshlrev_b64 v[16:17], 6, v[32:33]
	v_lshl_add_u64 v[16:17], s[60:61], 0, v[16:17]
	v_lshl_add_u64 v[16:17], s[48:49], 2, v[16:17]
	s_waitcnt lgkmcnt(0)
	v_add_f32_e32 v18, v20, v21
	global_store_dword v[16:17], v18, off
.LBB0_218:
	s_or_b64 exec, exec, s[50:51]
	v_add_u32_e32 v16, 0xb0, v160
	v_ashrrev_i32_e32 v17, 31, v16
	v_lshlrev_b64 v[18:19], s41, v[16:17]
	v_mul_f32_e32 v20, v13, v13
	v_lshl_add_u64 v[18:19], v[18:19], 1, v[162:163]
	v_fmac_f32_e32 v20, v12, v12
	v_mbcnt_lo_u32_b32 v252, -1, 0
	v_mbcnt_hi_u32_b32 v252, -1, v252
	v_and_b32_e32 v252, 16, v252
	v_lshrrev_b32_e32 v253, 1, v252
	v_add_u32_e32 v252, v252, v253
	v_mov_b32_e32 v253, 0
	v_cvt_pk_bf16_f32 v244, v12, v13
	v_cvt_pk_bf16_f32 v245, v14, v15
	s_nop 0
	v_mul_f32_e32 v12, v9, v9
	v_mul_f32_e32 v13, v11, v11
	s_waitcnt lgkmcnt(0)
	v_mul_f32_e32 v21, v15, v15
	v_fmac_f32_e32 v12, v8, v8
	v_fmac_f32_e32 v13, v10, v10
	v_fmac_f32_e32 v21, v14, v14
	v_add_f32_e32 v12, v12, v13
	v_cvt_pk_bf16_f32 v246, v8, v9
	v_mul_f32_e32 v9, v5, v5
	v_mul_f32_e32 v13, v7, v7
	v_add_f32_e32 v20, v20, v21
	v_fmac_f32_e32 v9, v4, v4
	v_fmac_f32_e32 v13, v6, v6
	v_add_f32_e32 v12, v20, v12
	v_add_f32_e32 v9, v9, v13
	v_add_f32_e32 v9, v12, v9
	v_mul_f32_e32 v12, v1, v1
	v_mul_f32_e32 v13, v3, v3
	v_fmac_f32_e32 v12, v0, v0
	v_fmac_f32_e32 v13, v2, v2
	v_add_f32_e32 v12, v12, v13
	v_add_f32_e32 v12, v9, v12
	ds_bpermute_b32 v13, v120, v12
	v_cvt_pk_bf16_f32 v247, v10, v11
	s_nop 1
	v_permlane16_swap_b32_e32 v244, v246
	v_permlane16_swap_b32_e32 v245, v247
	v_lshl_add_u64 v[242:243], v[18:19], 0, v[252:253]
	global_store_dwordx4 v[242:243], v[244:247], off sc0 sc1
	v_cvt_pk_bf16_f32 v248, v4, v5
	v_cvt_pk_bf16_f32 v249, v6, v7
	s_waitcnt lgkmcnt(0)
	v_add_f32_e32 v4, v12, v13
	ds_bpermute_b32 v5, v116, v4
	s_nop 0
	v_cvt_pk_bf16_f32 v250, v0, v1
	v_cvt_pk_bf16_f32 v251, v2, v3
	s_nop 1
	v_permlane16_swap_b32_e32 v248, v250
	v_permlane16_swap_b32_e32 v249, v251
	v_lshl_add_u64 v[242:243], v[18:19], 0, v[252:253]
	global_store_dwordx4 v[242:243], v[248:251], off offset:256 sc0 sc1
	s_and_saveexec_b64 s[50:51], s[4:5]
	s_cbranch_execz .LBB0_220
	v_lshlrev_b64 v[0:1], 6, v[16:17]
	v_lshl_add_u64 v[0:1], s[60:61], 0, v[0:1]
	v_lshl_add_u64 v[0:1], s[48:49], 2, v[0:1]
	s_waitcnt lgkmcnt(0)
	v_add_f32_e32 v2, v4, v5
	global_store_dword v[0:1], v2, off
